# P2b SQ/SK epilogue reads rope rows from an LDS copy (80B padded rows, DMA-filled in K-loop iteration 2) instead of 32 quarter-sector global loads
# baseline (speedup 1.0000x reference)
;     __device__ __forceinline__ void operator()(Acc& acc, const Unit& u, int wr, int wc, int fr, int fq) const {
;     ...
;                     for (int m2 = 0; m2 < 2; ++m2) { const float* rp = rope + (size_t)(row0 + ai * HALF + (2 * mh + m2) * 16) * 16;
; #pragma unroll
;                         for (int n = 0; n < 2; ++n) { rc[m2][n] = *(const f32x4*)(rp + 4 * n); rs[m2][n] = *(const f32x4*)(rp + 8 + 4 * n); } }
.LBB0_357:
	s_cmp_lg_u32 s45, 0
	s_cbranch_scc1 .Lrp_nofill
	s_cmp_eq_u32 s12, 1
	s_cbranch_scc1 .Lrp_nofill
	s_cmp_lt_u32 s40, 8
	s_cbranch_scc1 .Lrp_nofill
	v_lshrrev_b32_e32 v232, 6, v228
	s_lshl_b32 s98, s84, 14
	s_add_u32 s100, s92, 0x1e00000
	s_addc_u32 s101, s93, 0
	v_readfirstlane_b32 s99, v232
	s_add_u32 s100, s100, s98
	s_addc_u32 s101, s101, 0
	v_mul_u32_u24_e32 v234, 0x3334, v228
	v_lshrrev_b32_e32 v234, 16, v234
	v_mul_u32_u24_e32 v235, 5, v234
	v_sub_u32_e32 v235, v228, v235
	v_min_u32_e32 v235, 3, v235
	v_lshlrev_b32_e32 v235, 4, v235
	v_lshl_add_u32 v234, v234, 6, v235
	s_lshl_b32 s98, s99, 10
	s_add_i32 s98, s98, 0x20000
	s_mov_b32 m0, s98
	v_add_u32_e32 v233, 0x200, v228
	global_load_lds_dwordx4 v234, s[100:101]
	v_mul_u32_u24_e32 v236, 0x3334, v233
	v_lshrrev_b32_e32 v236, 16, v236
	v_mul_u32_u24_e32 v237, 5, v236
	v_sub_u32_e32 v237, v233, v237
	v_min_u32_e32 v237, 3, v237
	v_lshlrev_b32_e32 v237, 4, v237
	v_lshl_add_u32 v236, v236, 6, v237
	s_add_i32 m0, s98, 0x2000
	s_nop 0
	global_load_lds_dwordx4 v236, s[100:101]
	s_cmp_lt_u32 s99, 4
	s_cbranch_scc0 .Lrp_nofill
	v_add_u32_e32 v239, 0x400, v228
	v_mul_u32_u24_e32 v240, 0x3334, v239
	v_lshrrev_b32_e32 v240, 16, v240
	v_mul_u32_u24_e32 v241, 5, v240
	v_sub_u32_e32 v241, v239, v241
	v_min_u32_e32 v241, 3, v241
	v_lshlrev_b32_e32 v241, 4, v241
	v_lshl_add_u32 v238, v240, 6, v241
	s_add_i32 m0, s98, 0x4000
	s_nop 0
	global_load_lds_dwordx4 v238, s[100:101]

; __device__ __forceinline__ float frsq(float x) { return __builtin_amdgcn_rsqf(x); }
;     __device__ __forceinline__ void operator()(Acc& acc, const Unit& u, int wr, int wc, int fr, int fq) const {
;     ...
;             const bool isv = (pn == 10) && (wc >= 2);
;             if (isv || (DIS_MASK & 4)) {
; #pragma unroll
;                 for (int ai = 0; ai < 2; ++ai)
; #pragma unroll
;                     for (int m = 0; m < 4; ++m)
; #pragma unroll
;                         for (int bj = 0; bj < 2; ++bj) *(u32x4*)(SV + (size_t)(row0 + ai * HALF + m * 16) * 128 + (wc - 2) * 64 + bj * 32 + 8 * fq) = pack8(acc[ai][bj][m][0], acc[ai][bj][m][1]);
;             } else {
;                 const bool isk = (pn == 10);
;                 const float* gp = isk ? kng : qng; const float osc = isk ? 1.0f : 0.125f * 1.4426950408889634f;
;                 f32x4 g[2][2];
; #pragma unroll
;                 for (int bj = 0; bj < 2; ++bj)
; #pragma unroll
;                     for (int n = 0; n < 2; ++n) g[bj][n] = *(const f32x4*)(gp + bj * 32 + 8 * fq + 4 * n) * osc;
;                 bf16_t* ob = isk ? (SK + wc * 64 + 8 * fq) : (SQ + (pn - 8) * 256 + wc * 64 + 8 * fq); const int ld = isk ? 128 : 512;
; #pragma unroll
;                 for (int ai = 0; ai < 2; ++ai) {
; #pragma unroll
;                   for (int mh = 0; mh < 2; ++mh) {
;                     f32x4 rc[2][2], rs[2][2];
; #pragma unroll
;                     for (int m2 = 0; m2 < 2; ++m2) { const float* rp = rope + (size_t)(row0 + ai * HALF + (2 * mh + m2) * 16) * 16;
; #pragma unroll
;                         for (int n = 0; n < 2; ++n) { rc[m2][n] = *(const f32x4*)(rp + 4 * n); rs[m2][n] = *(const f32x4*)(rp + 8 + 4 * n); } }
;                     __builtin_amdgcn_sched_barrier(0);
; #pragma unroll
;                     for (int m2 = 0; m2 < 2; ++m2) { const int m = 2 * mh + m2;
;                         const int row = row0 + ai * HALF + m * 16;
;                         float ss = 0.f;
; #pragma unroll
;                         for (int bj = 0; bj < 2; ++bj)
; #pragma unroll
;                             for (int n = 0; n < 2; ++n) { const f32x4 v = acc[ai][bj][m][n]; ss += (v[0] * v[0] + v[1] * v[1]) + (v[2] * v[2] + v[3] * v[3]); }
;                         ss += __shfl_xor(ss, 16); ss += __shfl_xor(ss, 32);
;                         const float rstd = frsq(ss * (1.0f / 64.0f) + EPS);
.LBB0_360:
	s_mul_i32 s98, s84, 0x5000
	s_sub_u32 s98, 0x20000, s98
	v_mov_b32_e32 v219, v209
	v_mov_b32_e32 v128, v210
	s_lshl_b32 s4, s84, 8
	s_add_i32 s4, s4, s22
	v_lshlrev_b32_e32 v176, 3, v128
	v_add_u32_e32 v174, s4, v219
	v_add_u32_e32 v172, s23, v176
	s_cmp_lg_u32 s12, 1
	s_mov_b64 s[4:5], -1
	s_cbranch_scc0 .LBB0_383
	s_cmp_gt_i32 s40, 3
	s_cbranch_scc0 .LBB0_375
	s_cmp_gt_u32 s40, 5
	s_cbranch_scc0 .LBB0_372
	s_cmp_gt_u32 s40, 7
	s_cbranch_scc0 .LBB0_369
	s_cmp_eq_u32 s40, 10
	s_cselect_b64 s[70:71], -1, 0
	s_and_b64 s[48:49], s[70:71], s[52:53]
	s_andn2_b64 vcc, exec, s[48:49]
	v_ashrrev_i32_e32 v177, 31, v176
	s_cbranch_vccz .LBB0_366
	s_and_b64 s[4:5], s[70:71], exec
	s_mov_b64 s[4:5], s[62:63]
	s_mov_b32 s12, s55
	s_mov_b32 s35, s58
	s_mov_b64 s[80:81], s[52:53]
	v_readlane_b32 s48, v254, 24
	v_readlane_b32 s52, v254, 28
	v_readlane_b32 s53, v254, 29
	v_readlane_b32 s54, v254, 30
	v_readlane_b32 s55, v254, 31
	v_readlane_b32 s56, v254, 32
	v_readlane_b32 s57, v254, 33
	v_readlane_b32 s58, v254, 34
	v_readlane_b32 s59, v254, 35
	v_readlane_b32 s60, v254, 36
	v_readlane_b32 s61, v254, 37
	v_readlane_b32 s62, v254, 38
	v_readlane_b32 s63, v254, 39
	v_readlane_b32 s52, v254, 8
	v_readlane_b32 s49, v254, 25
	v_readlane_b32 s62, v254, 18
	v_readlane_b32 s63, v254, 19
	v_readlane_b32 s66, v254, 22
	v_readlane_b32 s67, v254, 23
	s_mov_b64 s[62:63], s[4:5]
	s_cselect_b32 s4, s49, s67
	s_cselect_b32 s5, s48, s66
	v_mov_b32_e32 v130, s5
	v_mov_b32_e32 v131, s4
	v_lshl_add_u64 v[140:141], v[176:177], 2, v[130:131]
	global_load_dwordx4 v[130:133], v[140:141], off offset:16
	global_load_dwordx4 v[134:137], v[140:141], off
	v_cndmask_b32_e64 v138, v216, 1.0, s[70:71]
	v_readlane_b32 s55, v254, 11
	s_lshl_b32 s4, s40, 8
	s_mov_b32 s55, s12
	s_add_i32 s12, s4, 0xfffff800
	s_lshl_b64 s[4:5], s[12:13], 1
	v_readlane_b32 s12, v254, 47
	v_readlane_b32 s58, v254, 14
	s_add_u32 s12, s12, s4
	v_readlane_b32 s4, v254, 48
	s_mov_b32 s58, s35
	s_addc_u32 s35, s4, s5
	v_xor_b32_e32 v129, 16, v217
	s_and_b64 s[4:5], s[70:71], exec
	v_readlane_b32 s4, v254, 49
	v_readlane_b32 s5, v254, 50
	s_cselect_b32 s4, s4, s12
	v_readlane_b32 s12, v254, 63
	v_readlane_b32 s50, v254, 26
	v_readlane_b32 s51, v254, 27
	s_cselect_b32 s5, s5, s35
	s_add_u32 s4, s4, s12
	s_addc_u32 s5, s5, 0
	v_ashrrev_i32_e32 v175, 31, v174
	v_readlane_b32 s50, v254, 57
	v_lshl_add_u64 v[178:179], v[176:177], 1, s[4:5]
	v_cmp_eq_u32_e64 s[4:5], 0, v128
	v_readlane_b32 s51, v254, 58
	v_add_u32_e32 v196, 16, v174
	v_ashrrev_i32_e32 v197, 31, v196
	v_readlane_b32 s53, v254, 9
	v_readlane_b32 s56, v254, 12
	v_readlane_b32 s57, v254, 13
	v_readlane_b32 s60, v254, 16
	v_readlane_b32 s61, v254, 17
	v_readlane_b32 s64, v254, 20
	v_readlane_b32 s65, v254, 21
	s_mov_b64 s[56:57], 0x4000
	s_mov_b64 s[64:65], 0x20000
	s_mov_b64 s[60:61], 0xc000
	s_mov_b64 s[52:53], s[80:81]
	s_mov_b64 s[66:67], 0x24000
	v_readlane_b32 s54, v254, 10
	v_readlane_b32 s59, v254, 15
	s_waitcnt vmcnt(0)
	v_pk_mul_f32 v[180:181], v[138:139], v[132:133] op_sel_hi:[0,1]
	v_pk_mul_f32 v[184:185], v[138:139], v[136:137] op_sel_hi:[0,1]
	v_pk_mul_f32 v[186:187], v[138:139], v[134:135] op_sel_hi:[0,1]
	v_pk_mul_f32 v[182:183], v[138:139], v[130:131] op_sel_hi:[0,1]
	global_load_dwordx4 v[130:133], v[140:141], off offset:144
	global_load_dwordx4 v[134:137], v[140:141], off offset:128
	s_waitcnt vmcnt(1)
	v_pk_mul_f32 v[190:191], v[138:139], v[130:131] op_sel_hi:[0,1]
	v_and_b32_e32 v130, 64, v217
	v_add_u32_e32 v130, 64, v130
	v_cmp_lt_i32_e32 vcc, v129, v130
	s_waitcnt vmcnt(0)
	v_pk_mul_f32 v[192:193], v[138:139], v[136:137] op_sel_hi:[0,1]
	v_pk_mul_f32 v[194:195], v[138:139], v[134:135] op_sel_hi:[0,1]
	v_cndmask_b32_e32 v129, v217, v129, vcc
	v_lshlrev_b32_e32 v173, 2, v129
	v_xor_b32_e32 v129, 32, v217
	v_cmp_lt_i32_e32 vcc, v129, v130
	v_pk_mul_f32 v[188:189], v[138:139], v[132:133] op_sel_hi:[0,1]
	s_nop 0
	v_cndmask_b32_e32 v129, v217, v129, vcc
	v_lshlrev_b32_e32 v220, 2, v129
	v_cmp_gt_i32_e32 vcc, 2, v128
	v_mul_u32_u24_e32 v232, 0x50, v174
	v_add_u32_e32 v232, s98, v232
	ds_read_b128 v[144:147], v232 offset:16
	ds_read_b128 v[148:151], v232 offset:48
	ds_read_b128 v[152:155], v232
	ds_read_b128 v[156:159], v232 offset:32
	v_mul_u32_u24_e32 v233, 0x50, v196
	v_add_u32_e32 v233, s98, v233
	ds_read_b128 v[128:131], v233 offset:16
	ds_read_b128 v[132:135], v233 offset:48
	ds_read_b128 v[136:139], v233
	s_nop 0
	ds_read_b128 v[140:143], v233 offset:32
	v_pk_mul_f32 v[198:199], v[126:127], v[126:127]
	v_pk_mul_f32 v[200:201], v[124:125], v[124:125]
	s_and_b64 s[48:49], s[70:71], exec
	v_pk_mov_b32 v[202:203], v[200:201], v[198:199] op_sel:[1,0]
	v_mov_b32_e32 v201, v199
	v_pk_add_f32 v[198:199], v[202:203], v[200:201]
	v_pk_mul_f32 v[200:201], v[122:123], v[122:123]
	v_pk_mul_f32 v[202:203], v[120:121], v[120:121]
	v_pk_add_f32 v[198:199], v[198:199], v[198:199] op_sel:[0,1] op_sel_hi:[1,0]
	v_pk_mov_b32 v[204:205], v[202:203], v[200:201] op_sel:[1,0]
	v_mov_b32_e32 v203, v201
	v_pk_add_f32 v[200:201], v[204:205], v[202:203]
	v_mul_f32_e32 v202, v104, v104
	v_mul_f32_e32 v203, v105, v105
	v_pk_add_f32 v[200:201], v[200:201], v[200:201] op_sel:[0,1] op_sel_hi:[1,0]
	v_mov_b32_e32 v199, v202
	v_mov_b32_e32 v201, v203
	v_pk_add_f32 v[198:199], v[198:199], v[200:201]
	v_mul_f32_e32 v200, v113, v113
	v_mul_f32_e32 v202, v115, v115
	v_mul_f32_e32 v204, v106, v106
	v_mul_f32_e32 v205, v107, v107
	v_pk_fma_f32 v[200:201], v[112:113], v[112:113], v[200:201] op_sel_hi:[1,1,0]
	v_pk_fma_f32 v[202:203], v[114:115], v[114:115], v[202:203] op_sel_hi:[1,1,0]
	v_mov_b32_e32 v201, v204
	v_mov_b32_e32 v203, v205
	v_pk_add_f32 v[200:201], v[200:201], v[202:203]
	s_cselect_b32 s12, 7, 9
	v_pk_add_f32 v[198:199], v[198:199], v[200:201]
	s_nop 0
	v_add_f32_e32 v198, v198, v199
	ds_bpermute_b32 v199, v173, v198
	s_waitcnt lgkmcnt(0)
; __device__ __forceinline__ u32x4 pack8(const f32x4& a, const f32x4& b) { u32x4 w; w.x = cvt_pk_bf16(a[0], a[1]); w.y = cvt_pk_bf16(a[2], a[3]); w.z = cvt_pk_bf16(b[0], b[1]); w.w = cvt_pk_bf16(b[2], b[3]); return w; }
; __device__ __forceinline__ float frsq(float x) { return __builtin_amdgcn_rsqf(x); }
;     __device__ __forceinline__ void operator()(Acc& acc, const Unit& u, int wr, int wc, int fr, int fq) const {
;     ...
;                     for (int m2 = 0; m2 < 2; ++m2) { const int m = 2 * mh + m2;
;                         const int row = row0 + ai * HALF + m * 16;
;                         float ss = 0.f;
; #pragma unroll
;                         for (int bj = 0; bj < 2; ++bj)
; #pragma unroll
;                             for (int n = 0; n < 2; ++n) { const f32x4 v = acc[ai][bj][m][n]; ss += (v[0] * v[0] + v[1] * v[1]) + (v[2] * v[2] + v[3] * v[3]); }
;                         ss += __shfl_xor(ss, 16); ss += __shfl_xor(ss, 32);
;                         const float rstd = frsq(ss * (1.0f / 64.0f) + EPS);
;                         f32x4 y[2][2];
; #pragma unroll
;                         for (int bj = 0; bj < 2; ++bj)
; #pragma unroll
;                             for (int n = 0; n < 2; ++n) y[bj][n] = acc[ai][bj][m][n] * rstd * g[bj][n];
; #pragma unroll
;                         for (int n = 0; n < 2; ++n) {
;                             const f32x4 cs = rc[m2][n], sn = rs[m2][n];
;                             f32x4 o;
; #pragma unroll
;                             for (int i = 0; i < 4; ++i) { const float mine = y[0][n][i], oth = __shfl_xor(mine, 16);
;                                 const float r = (fq == 0) ? (mine * cs[i] - oth * sn[i]) : (mine * cs[i] + oth * sn[i]);
;                                 o[i] = (fq < 2) ? r : mine; }
;                             y[0][n] = o;
;                         }
; #pragma unroll
;                         for (int bj = 0; bj < 2; ++bj) *(u32x4*)(ob + (size_t)row * ld + bj * 32) = pack8(y[bj][0], y[bj][1]);
	v_add_f32_e32 v198, v198, v199
	ds_bpermute_b32 v199, v220, v198
	s_waitcnt lgkmcnt(0)
	v_add_f32_e32 v198, v198, v199
	v_fmamk_f32 v198, v198, 0x3c800000, v215
	v_rsq_f32_e32 v202, v198
	s_nop 0
	v_pk_mul_f32 v[198:199], v[124:125], v[202:203] op_sel_hi:[1,0]
	s_nop 0
	v_pk_mul_f32 v[224:225], v[186:187], v[198:199]
	ds_bpermute_b32 v221, v173, v224
	v_pk_mul_f32 v[200:201], v[126:127], v[202:203] op_sel_hi:[1,0]
	v_pk_mul_f32 v[198:199], v[120:121], v[202:203] op_sel_hi:[1,0]
	v_pk_mul_f32 v[222:223], v[184:185], v[200:201]
	v_pk_mul_f32 v[226:227], v[182:183], v[198:199]
	s_waitcnt vmcnt(4) lgkmcnt(0)
	v_mul_f32_e32 v156, v156, v221
	v_cndmask_b32_e64 v156, v156, -v156, s[4:5]
	v_fmac_f32_e32 v156, v152, v224
	v_cndmask_b32_e32 v152, v224, v156, vcc
	ds_bpermute_b32 v156, v173, v225
	v_pk_mul_f32 v[200:201], v[122:123], v[202:203] op_sel_hi:[1,0]
	v_pk_mul_f32 v[198:199], v[114:115], v[202:203] op_sel_hi:[1,0]
	v_pk_mul_f32 v[206:207], v[180:181], v[200:201]
	v_pk_mul_f32 v[200:201], v[112:113], v[202:203] op_sel_hi:[1,0]
	s_waitcnt lgkmcnt(0)
	v_mul_f32_e32 v156, v157, v156
	v_cndmask_b32_e64 v156, v156, -v156, s[4:5]
	v_fmac_f32_e32 v156, v153, v225
	v_cndmask_b32_e32 v153, v225, v156, vcc
	ds_bpermute_b32 v156, v173, v222
	v_pk_mul_f32 v[204:205], v[104:105], v[202:203] op_sel_hi:[1,0]
	v_pk_mul_f32 v[202:203], v[106:107], v[202:203] op_sel_hi:[1,0]
	v_pk_mul_f32 v[198:199], v[192:193], v[198:199]
	v_pk_mul_f32 v[200:201], v[194:195], v[200:201]
	s_waitcnt lgkmcnt(0)
	v_mul_f32_e32 v156, v158, v156
	v_cndmask_b32_e64 v156, v156, -v156, s[4:5]
	v_fmac_f32_e32 v156, v154, v222
	v_cndmask_b32_e32 v154, v222, v156, vcc
	ds_bpermute_b32 v156, v173, v223
	v_pk_mul_f32 v[202:203], v[188:189], v[202:203]
	v_pk_mul_f32 v[204:205], v[190:191], v[204:205]
	s_waitcnt lgkmcnt(0)
	v_mul_f32_e32 v156, v159, v156
	v_cndmask_b32_e64 v156, v156, -v156, s[4:5]
	v_fmac_f32_e32 v156, v155, v223
	v_cndmask_b32_e32 v155, v223, v156, vcc
	ds_bpermute_b32 v156, v173, v226
	s_waitcnt lgkmcnt(0)
	v_mul_f32_e32 v148, v148, v156
	v_cndmask_b32_e64 v148, v148, -v148, s[4:5]
	v_fmac_f32_e32 v148, v144, v226
	ds_bpermute_b32 v144, v173, v227
	v_cndmask_b32_e32 v156, v226, v148, vcc
	s_waitcnt lgkmcnt(0)
	v_mul_f32_e32 v144, v149, v144
	v_cndmask_b32_e64 v144, v144, -v144, s[4:5]
	v_fmac_f32_e32 v144, v145, v227
	v_cndmask_b32_e32 v157, v227, v144, vcc
	ds_bpermute_b32 v144, v173, v206
	s_waitcnt lgkmcnt(0)
	v_mul_f32_e32 v144, v150, v144
	v_cndmask_b32_e64 v144, v144, -v144, s[4:5]
	v_fmac_f32_e32 v144, v146, v206
	v_cndmask_b32_e32 v150, v206, v144, vcc
	ds_bpermute_b32 v144, v173, v207
	s_waitcnt lgkmcnt(0)
	v_mul_f32_e32 v144, v151, v144
	v_cndmask_b32_e64 v144, v144, -v144, s[4:5]
	v_fmac_f32_e32 v144, v147, v207
	v_cndmask_b32_e32 v147, v207, v144, vcc
	v_lshlrev_b64 v[144:145], s12, v[174:175]
	v_lshl_add_u64 v[148:149], v[144:145], 1, v[178:179]
	v_cvt_pk_bf16_f32 v144, v152, v153
	v_cvt_pk_bf16_f32 v145, v154, v155
	v_cvt_pk_bf16_f32 v146, v156, v157
	v_cvt_pk_bf16_f32 v147, v150, v147
	global_store_dwordx4 v[148:149], v[144:147], off
	s_nop 1
	v_cvt_pk_bf16_f32 v144, v200, v201
	v_cvt_pk_bf16_f32 v145, v198, v199
	v_cvt_pk_bf16_f32 v146, v204, v205
	v_cvt_pk_bf16_f32 v147, v202, v203
	global_store_dwordx4 v[148:149], v[144:147], off offset:64
	s_nop 1
	v_pk_mul_f32 v[144:145], v[118:119], v[118:119]
	v_pk_mul_f32 v[146:147], v[116:117], v[116:117]
	s_nop 0
	v_pk_mov_b32 v[148:149], v[146:147], v[144:145] op_sel:[1,0]
	v_mov_b32_e32 v147, v145
	v_pk_add_f32 v[144:145], v[148:149], v[146:147]
	v_pk_mul_f32 v[146:147], v[110:111], v[110:111]
	v_pk_mul_f32 v[148:149], v[108:109], v[108:109]
	v_pk_add_f32 v[144:145], v[144:145], v[144:145] op_sel:[0,1] op_sel_hi:[1,0]
	v_pk_mov_b32 v[150:151], v[148:149], v[146:147] op_sel:[1,0]
	v_mov_b32_e32 v149, v147
	v_pk_add_f32 v[146:147], v[150:151], v[148:149]
	v_mul_f32_e32 v148, v88, v88
	v_mul_f32_e32 v149, v89, v89
	v_pk_add_f32 v[146:147], v[146:147], v[146:147] op_sel:[0,1] op_sel_hi:[1,0]
	v_mov_b32_e32 v145, v148
	v_mov_b32_e32 v147, v149
	v_pk_add_f32 v[144:145], v[144:145], v[146:147]
	v_mul_f32_e32 v146, v97, v97
	v_mul_f32_e32 v148, v99, v99
	v_mul_f32_e32 v150, v90, v90
	v_mul_f32_e32 v151, v91, v91
	v_pk_fma_f32 v[146:147], v[96:97], v[96:97], v[146:147] op_sel_hi:[1,1,0]
	v_pk_fma_f32 v[148:149], v[98:99], v[98:99], v[148:149] op_sel_hi:[1,1,0]
	v_mov_b32_e32 v147, v150
	v_mov_b32_e32 v149, v151
	v_pk_add_f32 v[146:147], v[146:147], v[148:149]
	s_nop 0
	v_pk_add_f32 v[144:145], v[144:145], v[146:147]
	s_nop 0
	v_add_f32_e32 v144, v144, v145
	ds_bpermute_b32 v145, v173, v144
	s_waitcnt lgkmcnt(0)
	v_add_f32_e32 v144, v144, v145
	ds_bpermute_b32 v145, v220, v144
	s_waitcnt lgkmcnt(0)
	v_add_f32_e32 v144, v144, v145
	v_fmamk_f32 v144, v144, 0x3c800000, v215
	v_rsq_f32_e32 v144, v144
	s_nop 0
	v_pk_mul_f32 v[146:147], v[116:117], v[144:145] op_sel_hi:[1,0]
	s_nop 0
	v_pk_mul_f32 v[156:157], v[186:187], v[146:147]
	ds_bpermute_b32 v175, v173, v156
	v_pk_mul_f32 v[148:149], v[118:119], v[144:145] op_sel_hi:[1,0]
	v_pk_mul_f32 v[146:147], v[108:109], v[144:145] op_sel_hi:[1,0]
	v_pk_mul_f32 v[154:155], v[184:185], v[148:149]
	v_pk_mul_f32 v[158:159], v[182:183], v[146:147]
	s_waitcnt vmcnt(2) lgkmcnt(0)
	v_mul_f32_e32 v140, v140, v175
	v_cndmask_b32_e64 v140, v140, -v140, s[4:5]
	v_fmac_f32_e32 v140, v136, v156
	v_cndmask_b32_e32 v136, v156, v140, vcc
	ds_bpermute_b32 v140, v173, v157
	v_pk_mul_f32 v[148:149], v[110:111], v[144:145] op_sel_hi:[1,0]
	v_pk_mul_f32 v[146:147], v[98:99], v[144:145] op_sel_hi:[1,0]
	v_pk_mul_f32 v[152:153], v[180:181], v[148:149]
	v_pk_mul_f32 v[148:149], v[96:97], v[144:145] op_sel_hi:[1,0]
	s_waitcnt lgkmcnt(0)
; __device__ __forceinline__ u32x4 pack8(const f32x4& a, const f32x4& b) { u32x4 w; w.x = cvt_pk_bf16(a[0], a[1]); w.y = cvt_pk_bf16(a[2], a[3]); w.z = cvt_pk_bf16(b[0], b[1]); w.w = cvt_pk_bf16(b[2], b[3]); return w; }
; __device__ __forceinline__ float frsq(float x) { return __builtin_amdgcn_rsqf(x); }
;     __device__ __forceinline__ void operator()(Acc& acc, const Unit& u, int wr, int wc, int fr, int fq) const {
;     ...
;                     for (int m2 = 0; m2 < 2; ++m2) { const float* rp = rope + (size_t)(row0 + ai * HALF + (2 * mh + m2) * 16) * 16;
; #pragma unroll
;                         for (int n = 0; n < 2; ++n) { rc[m2][n] = *(const f32x4*)(rp + 4 * n); rs[m2][n] = *(const f32x4*)(rp + 8 + 4 * n); } }
;                     __builtin_amdgcn_sched_barrier(0);
; #pragma unroll
;                     for (int m2 = 0; m2 < 2; ++m2) { const int m = 2 * mh + m2;
;                         const int row = row0 + ai * HALF + m * 16;
;                         float ss = 0.f;
; #pragma unroll
;                         for (int bj = 0; bj < 2; ++bj)
; #pragma unroll
;                             for (int n = 0; n < 2; ++n) { const f32x4 v = acc[ai][bj][m][n]; ss += (v[0] * v[0] + v[1] * v[1]) + (v[2] * v[2] + v[3] * v[3]); }
;                         ss += __shfl_xor(ss, 16); ss += __shfl_xor(ss, 32);
;                         const float rstd = frsq(ss * (1.0f / 64.0f) + EPS);
;                         f32x4 y[2][2];
; #pragma unroll
;                         for (int bj = 0; bj < 2; ++bj)
; #pragma unroll
;                             for (int n = 0; n < 2; ++n) y[bj][n] = acc[ai][bj][m][n] * rstd * g[bj][n];
; #pragma unroll
;                         for (int n = 0; n < 2; ++n) {
;                             const f32x4 cs = rc[m2][n], sn = rs[m2][n];
;                             f32x4 o;
; #pragma unroll
;                             for (int i = 0; i < 4; ++i) { const float mine = y[0][n][i], oth = __shfl_xor(mine, 16);
;                                 const float r = (fq == 0) ? (mine * cs[i] - oth * sn[i]) : (mine * cs[i] + oth * sn[i]);
;                                 o[i] = (fq < 2) ? r : mine; }
;                             y[0][n] = o;
;                         }
; #pragma unroll
;                         for (int bj = 0; bj < 2; ++bj) *(u32x4*)(ob + (size_t)row * ld + bj * 32) = pack8(y[bj][0], y[bj][1]);
	v_mul_f32_e32 v140, v141, v140
	v_cndmask_b32_e64 v140, v140, -v140, s[4:5]
	v_fmac_f32_e32 v140, v137, v157
	v_cndmask_b32_e32 v137, v157, v140, vcc
	ds_bpermute_b32 v140, v173, v154
	v_pk_mul_f32 v[146:147], v[192:193], v[146:147]
	v_pk_mul_f32 v[150:151], v[194:195], v[148:149]
	v_pk_mul_f32 v[148:149], v[88:89], v[144:145] op_sel_hi:[1,0]
	v_pk_mul_f32 v[144:145], v[90:91], v[144:145] op_sel_hi:[1,0]
	s_waitcnt lgkmcnt(0)
	v_mul_f32_e32 v140, v142, v140
	v_cndmask_b32_e64 v140, v140, -v140, s[4:5]
	v_fmac_f32_e32 v140, v138, v154
	v_cndmask_b32_e32 v138, v154, v140, vcc
	ds_bpermute_b32 v140, v173, v155
	v_add_u32_e32 v154, 32, v174
	v_pk_mul_f32 v[144:145], v[188:189], v[144:145]
	v_pk_mul_f32 v[148:149], v[190:191], v[148:149]
	s_waitcnt lgkmcnt(0)
	v_mul_f32_e32 v140, v143, v140
	v_cndmask_b32_e64 v140, v140, -v140, s[4:5]
	v_fmac_f32_e32 v140, v139, v155
	v_cndmask_b32_e32 v139, v155, v140, vcc
	ds_bpermute_b32 v140, v173, v158
	v_ashrrev_i32_e32 v155, 31, v154
	s_waitcnt lgkmcnt(0)
	v_mul_f32_e32 v132, v132, v140
	v_cndmask_b32_e64 v132, v132, -v132, s[4:5]
	v_fmac_f32_e32 v132, v128, v158
	ds_bpermute_b32 v128, v173, v159
	v_cndmask_b32_e32 v140, v158, v132, vcc
	s_waitcnt lgkmcnt(0)
	v_mul_f32_e32 v128, v133, v128
	v_cndmask_b32_e64 v128, v128, -v128, s[4:5]
	v_fmac_f32_e32 v128, v129, v159
	v_cndmask_b32_e32 v141, v159, v128, vcc
	ds_bpermute_b32 v128, v173, v152
	s_waitcnt lgkmcnt(0)
	v_mul_f32_e32 v128, v134, v128
	v_cndmask_b32_e64 v128, v128, -v128, s[4:5]
	v_fmac_f32_e32 v128, v130, v152
	v_cndmask_b32_e32 v134, v152, v128, vcc
	ds_bpermute_b32 v128, v173, v153
	v_add_u32_e32 v152, 48, v174
	s_waitcnt lgkmcnt(0)
	v_mul_f32_e32 v128, v135, v128
	v_cndmask_b32_e64 v128, v128, -v128, s[4:5]
	v_fmac_f32_e32 v128, v131, v153
	v_cndmask_b32_e32 v131, v153, v128, vcc
	v_lshlrev_b64 v[128:129], s12, v[196:197]
	v_lshl_add_u64 v[132:133], v[128:129], 1, v[178:179]
	v_cvt_pk_bf16_f32 v128, v136, v137
	v_cvt_pk_bf16_f32 v129, v138, v139
	v_cvt_pk_bf16_f32 v130, v140, v141
	v_cvt_pk_bf16_f32 v131, v134, v131
	global_store_dwordx4 v[132:133], v[128:131], off
	v_ashrrev_i32_e32 v153, 31, v152
	s_nop 0
	v_cvt_pk_bf16_f32 v128, v150, v151
	v_cvt_pk_bf16_f32 v129, v146, v147
	v_cvt_pk_bf16_f32 v130, v148, v149
	v_cvt_pk_bf16_f32 v131, v144, v145
	global_store_dwordx4 v[132:133], v[128:131], off offset:64
	s_nop 1
	v_mul_u32_u24_e32 v232, 0x50, v154
	v_add_u32_e32 v232, s98, v232
	ds_read_b128 v[144:147], v232 offset:16
	ds_read_b128 v[148:151], v232 offset:48
	ds_read_b128 v[202:205], v232
	ds_read_b128 v[222:225], v232 offset:32
	v_mul_u32_u24_e32 v233, 0x50, v152
	v_add_u32_e32 v233, s98, v233
	ds_read_b128 v[128:131], v233 offset:16
	ds_read_b128 v[132:135], v233 offset:48
	ds_read_b128 v[136:139], v233
	s_nop 0
	ds_read_b128 v[140:143], v233 offset:32
	v_pk_mul_f32 v[156:157], v[102:103], v[102:103]
	v_pk_mul_f32 v[158:159], v[100:101], v[100:101]
	v_mul_f32_e32 v175, v72, v72
	v_pk_mov_b32 v[196:197], v[158:159], v[156:157] op_sel:[1,0]
	v_mov_b32_e32 v159, v157
	v_pk_add_f32 v[156:157], v[196:197], v[158:159]
	v_pk_mul_f32 v[158:159], v[94:95], v[94:95]
	v_pk_mul_f32 v[196:197], v[92:93], v[92:93]
	v_pk_add_f32 v[156:157], v[156:157], v[156:157] op_sel:[0,1] op_sel_hi:[1,0]
	v_pk_mov_b32 v[198:199], v[196:197], v[158:159] op_sel:[1,0]
	v_mov_b32_e32 v197, v159
	v_pk_add_f32 v[158:159], v[198:199], v[196:197]
	v_mul_f32_e32 v196, v73, v73
	v_pk_add_f32 v[158:159], v[158:159], v[158:159] op_sel:[0,1] op_sel_hi:[1,0]
	v_mov_b32_e32 v157, v175
	v_mov_b32_e32 v159, v196
	v_pk_add_f32 v[156:157], v[156:157], v[158:159]
	v_mul_f32_e32 v158, v81, v81
	v_mul_f32_e32 v197, v74, v74
	v_pk_fma_f32 v[158:159], v[80:81], v[80:81], v[158:159] op_sel_hi:[1,1,0]
	v_mul_f32_e32 v196, v83, v83
	v_mul_f32_e32 v198, v75, v75
	v_mov_b32_e32 v159, v197
	v_pk_fma_f32 v[196:197], v[82:83], v[82:83], v[196:197] op_sel_hi:[1,1,0]
	s_nop 0
	v_mov_b32_e32 v197, v198
	v_pk_add_f32 v[158:159], v[158:159], v[196:197]
	s_nop 0
	v_pk_add_f32 v[156:157], v[156:157], v[158:159]
	s_nop 0
	v_add_f32_e32 v156, v156, v157
	ds_bpermute_b32 v157, v173, v156
	s_waitcnt lgkmcnt(0)
	v_add_f32_e32 v156, v156, v157
	ds_bpermute_b32 v157, v220, v156
	s_waitcnt lgkmcnt(0)
	v_add_f32_e32 v156, v156, v157
	v_fmamk_f32 v156, v156, 0x3c800000, v215
	v_rsq_f32_e32 v196, v156
	s_nop 0
	v_pk_mul_f32 v[156:157], v[100:101], v[196:197] op_sel_hi:[1,0]
	s_nop 0
	v_pk_mul_f32 v[226:227], v[186:187], v[156:157]
	ds_bpermute_b32 v175, v173, v226
	v_pk_mul_f32 v[158:159], v[102:103], v[196:197] op_sel_hi:[1,0]
	v_pk_mul_f32 v[156:157], v[92:93], v[196:197] op_sel_hi:[1,0]
	v_pk_mul_f32 v[206:207], v[184:185], v[158:159]
	v_pk_mul_f32 v[230:231], v[182:183], v[156:157]
	s_waitcnt vmcnt(4) lgkmcnt(0)
	v_mul_f32_e32 v175, v222, v175
	v_cndmask_b32_e64 v175, v175, -v175, s[4:5]
	v_fmac_f32_e32 v175, v202, v226
	ds_bpermute_b32 v202, v173, v227
	v_pk_mul_f32 v[158:159], v[94:95], v[196:197] op_sel_hi:[1,0]
	v_pk_mul_f32 v[156:157], v[82:83], v[196:197] op_sel_hi:[1,0]
	v_pk_mul_f32 v[200:201], v[180:181], v[158:159]
	v_pk_mul_f32 v[158:159], v[80:81], v[196:197] op_sel_hi:[1,0]
	s_waitcnt lgkmcnt(0)
	v_mul_f32_e32 v202, v223, v202
	v_cndmask_b32_e64 v202, v202, -v202, s[4:5]
	v_fmac_f32_e32 v202, v203, v227
	ds_bpermute_b32 v203, v173, v206
	v_pk_mul_f32 v[198:199], v[72:73], v[196:197] op_sel_hi:[1,0]
	v_pk_mul_f32 v[196:197], v[74:75], v[196:197] op_sel_hi:[1,0]
	v_cndmask_b32_e32 v175, v226, v175, vcc
	v_cndmask_b32_e32 v202, v227, v202, vcc
	s_waitcnt lgkmcnt(0)
; __device__ __forceinline__ u32x4 pack8(const f32x4& a, const f32x4& b) { u32x4 w; w.x = cvt_pk_bf16(a[0], a[1]); w.y = cvt_pk_bf16(a[2], a[3]); w.z = cvt_pk_bf16(b[0], b[1]); w.w = cvt_pk_bf16(b[2], b[3]); return w; }
; __device__ __forceinline__ float frsq(float x) { return __builtin_amdgcn_rsqf(x); }
;     __device__ __forceinline__ void operator()(Acc& acc, const Unit& u, int wr, int wc, int fr, int fq) const {
;     ...
;                     for (int m2 = 0; m2 < 2; ++m2) { const int m = 2 * mh + m2;
;                         const int row = row0 + ai * HALF + m * 16;
;                         float ss = 0.f;
; #pragma unroll
;                         for (int bj = 0; bj < 2; ++bj)
; #pragma unroll
;                             for (int n = 0; n < 2; ++n) { const f32x4 v = acc[ai][bj][m][n]; ss += (v[0] * v[0] + v[1] * v[1]) + (v[2] * v[2] + v[3] * v[3]); }
;                         ss += __shfl_xor(ss, 16); ss += __shfl_xor(ss, 32);
;                         const float rstd = frsq(ss * (1.0f / 64.0f) + EPS);
;                         f32x4 y[2][2];
; #pragma unroll
;                         for (int bj = 0; bj < 2; ++bj)
; #pragma unroll
;                             for (int n = 0; n < 2; ++n) y[bj][n] = acc[ai][bj][m][n] * rstd * g[bj][n];
; #pragma unroll
;                         for (int n = 0; n < 2; ++n) {
;                             const f32x4 cs = rc[m2][n], sn = rs[m2][n];
;                             f32x4 o;
; #pragma unroll
;                             for (int i = 0; i < 4; ++i) { const float mine = y[0][n][i], oth = __shfl_xor(mine, 16);
;                                 const float r = (fq == 0) ? (mine * cs[i] - oth * sn[i]) : (mine * cs[i] + oth * sn[i]);
;                                 o[i] = (fq < 2) ? r : mine; }
;                             y[0][n] = o;
;                         }
; #pragma unroll
;                         for (int bj = 0; bj < 2; ++bj) *(u32x4*)(ob + (size_t)row * ld + bj * 32) = pack8(y[bj][0], y[bj][1]);
	v_mul_f32_e32 v203, v224, v203
	v_cndmask_b32_e64 v203, v203, -v203, s[4:5]
	v_fmac_f32_e32 v203, v204, v206
	ds_bpermute_b32 v204, v173, v207
	v_cndmask_b32_e32 v203, v206, v203, vcc
	v_pk_mul_f32 v[156:157], v[192:193], v[156:157]
	v_pk_mul_f32 v[158:159], v[194:195], v[158:159]
	v_pk_mul_f32 v[196:197], v[188:189], v[196:197]
	s_waitcnt lgkmcnt(0)
	v_mul_f32_e32 v204, v225, v204
	v_cndmask_b32_e64 v204, v204, -v204, s[4:5]
	v_fmac_f32_e32 v204, v205, v207
	ds_bpermute_b32 v205, v173, v230
	v_cndmask_b32_e32 v204, v207, v204, vcc
	v_pk_mul_f32 v[198:199], v[190:191], v[198:199]
	s_waitcnt lgkmcnt(0)
	v_mul_f32_e32 v148, v148, v205
	v_cndmask_b32_e64 v148, v148, -v148, s[4:5]
	v_fmac_f32_e32 v148, v144, v230
	ds_bpermute_b32 v144, v173, v231
	v_cndmask_b32_e32 v205, v230, v148, vcc
	s_waitcnt lgkmcnt(0)
	v_mul_f32_e32 v144, v149, v144
	v_cndmask_b32_e64 v144, v144, -v144, s[4:5]
	v_fmac_f32_e32 v144, v145, v231
	v_cndmask_b32_e32 v206, v231, v144, vcc
	ds_bpermute_b32 v144, v173, v200
	s_waitcnt lgkmcnt(0)
	v_mul_f32_e32 v144, v150, v144
	v_cndmask_b32_e64 v144, v144, -v144, s[4:5]
	v_fmac_f32_e32 v144, v146, v200
	v_cndmask_b32_e32 v150, v200, v144, vcc
	ds_bpermute_b32 v144, v173, v201
	s_waitcnt lgkmcnt(0)
	v_mul_f32_e32 v144, v151, v144
	v_cndmask_b32_e64 v144, v144, -v144, s[4:5]
	v_fmac_f32_e32 v144, v147, v201
	v_cndmask_b32_e32 v147, v201, v144, vcc
	v_lshlrev_b64 v[144:145], s12, v[154:155]
	v_lshl_add_u64 v[148:149], v[144:145], 1, v[178:179]
	v_cvt_pk_bf16_f32 v144, v175, v202
	v_cvt_pk_bf16_f32 v145, v203, v204
	v_cvt_pk_bf16_f32 v146, v205, v206
	v_cvt_pk_bf16_f32 v147, v150, v147
	global_store_dwordx4 v[148:149], v[144:147], off
	s_nop 1
	v_cvt_pk_bf16_f32 v144, v158, v159
	v_cvt_pk_bf16_f32 v145, v156, v157
	v_cvt_pk_bf16_f32 v146, v198, v199
	v_cvt_pk_bf16_f32 v147, v196, v197
	global_store_dwordx4 v[148:149], v[144:147], off offset:64
	s_nop 1
	v_pk_mul_f32 v[144:145], v[86:87], v[86:87]
	v_pk_mul_f32 v[146:147], v[84:85], v[84:85]
	s_nop 0
	v_pk_mov_b32 v[148:149], v[146:147], v[144:145] op_sel:[1,0]
	v_mov_b32_e32 v147, v145
	v_pk_add_f32 v[144:145], v[148:149], v[146:147]
	v_pk_mul_f32 v[146:147], v[78:79], v[78:79]
	v_pk_mul_f32 v[148:149], v[76:77], v[76:77]
	v_pk_add_f32 v[144:145], v[144:145], v[144:145] op_sel:[0,1] op_sel_hi:[1,0]
	v_pk_mov_b32 v[150:151], v[148:149], v[146:147] op_sel:[1,0]
	v_mov_b32_e32 v149, v147
	v_pk_add_f32 v[146:147], v[150:151], v[148:149]
	v_mul_f32_e32 v148, v64, v64
	v_mul_f32_e32 v149, v65, v65
	v_pk_add_f32 v[146:147], v[146:147], v[146:147] op_sel:[0,1] op_sel_hi:[1,0]
	v_mov_b32_e32 v145, v148
	v_mov_b32_e32 v147, v149
	v_pk_add_f32 v[144:145], v[144:145], v[146:147]
	v_mul_f32_e32 v146, v69, v69
	v_mul_f32_e32 v148, v71, v71
	v_mul_f32_e32 v150, v66, v66
	v_mul_f32_e32 v151, v67, v67
	v_pk_fma_f32 v[146:147], v[68:69], v[68:69], v[146:147] op_sel_hi:[1,1,0]
	v_pk_fma_f32 v[148:149], v[70:71], v[70:71], v[148:149] op_sel_hi:[1,1,0]
	v_mov_b32_e32 v147, v150
	v_mov_b32_e32 v149, v151
	v_pk_add_f32 v[146:147], v[146:147], v[148:149]
	s_nop 0
	v_pk_add_f32 v[144:145], v[144:145], v[146:147]
	s_nop 0
	v_add_f32_e32 v144, v144, v145
	ds_bpermute_b32 v145, v173, v144
	s_waitcnt lgkmcnt(0)
	v_add_f32_e32 v144, v144, v145
	ds_bpermute_b32 v145, v220, v144
	s_waitcnt lgkmcnt(0)
	v_add_f32_e32 v144, v144, v145
	v_fmamk_f32 v144, v144, 0x3c800000, v215
	v_rsq_f32_e32 v144, v144
	s_nop 0
	v_pk_mul_f32 v[146:147], v[84:85], v[144:145] op_sel_hi:[1,0]
	s_nop 0
	v_pk_mul_f32 v[158:159], v[186:187], v[146:147]
	ds_bpermute_b32 v175, v173, v158
	v_pk_mul_f32 v[148:149], v[86:87], v[144:145] op_sel_hi:[1,0]
	v_pk_mul_f32 v[146:147], v[76:77], v[144:145] op_sel_hi:[1,0]
	v_pk_mul_f32 v[156:157], v[184:185], v[148:149]
	v_pk_mul_f32 v[196:197], v[182:183], v[146:147]
	s_waitcnt vmcnt(2) lgkmcnt(0)
	v_mul_f32_e32 v140, v140, v175
	v_cndmask_b32_e64 v140, v140, -v140, s[4:5]
	v_fmac_f32_e32 v140, v136, v158
	v_cndmask_b32_e32 v136, v158, v140, vcc
	ds_bpermute_b32 v140, v173, v159
	v_pk_mul_f32 v[148:149], v[78:79], v[144:145] op_sel_hi:[1,0]
	v_pk_mul_f32 v[146:147], v[70:71], v[144:145] op_sel_hi:[1,0]
	v_pk_mul_f32 v[154:155], v[180:181], v[148:149]
	v_pk_mul_f32 v[148:149], v[68:69], v[144:145] op_sel_hi:[1,0]
	s_waitcnt lgkmcnt(0)
	v_mul_f32_e32 v140, v141, v140
	v_cndmask_b32_e64 v140, v140, -v140, s[4:5]
	v_fmac_f32_e32 v140, v137, v159
	v_cndmask_b32_e32 v137, v159, v140, vcc
	ds_bpermute_b32 v140, v173, v156
	v_pk_mul_f32 v[146:147], v[192:193], v[146:147]
	v_pk_mul_f32 v[150:151], v[194:195], v[148:149]
	v_pk_mul_f32 v[148:149], v[64:65], v[144:145] op_sel_hi:[1,0]
	v_pk_mul_f32 v[144:145], v[66:67], v[144:145] op_sel_hi:[1,0]
	s_waitcnt lgkmcnt(0)
	v_mul_f32_e32 v140, v142, v140
	v_cndmask_b32_e64 v140, v140, -v140, s[4:5]
	v_fmac_f32_e32 v140, v138, v156
	v_cndmask_b32_e32 v138, v156, v140, vcc
	ds_bpermute_b32 v140, v173, v157
	v_pk_mul_f32 v[144:145], v[188:189], v[144:145]
	v_pk_mul_f32 v[148:149], v[190:191], v[148:149]
	s_waitcnt lgkmcnt(0)
	v_mul_f32_e32 v140, v143, v140
	v_cndmask_b32_e64 v140, v140, -v140, s[4:5]
	v_fmac_f32_e32 v140, v139, v157
	v_cndmask_b32_e32 v139, v157, v140, vcc
	ds_bpermute_b32 v140, v173, v196
	s_waitcnt lgkmcnt(0)
	v_mul_f32_e32 v132, v132, v140
	v_cndmask_b32_e64 v132, v132, -v132, s[4:5]
	v_fmac_f32_e32 v132, v128, v196
	ds_bpermute_b32 v128, v173, v197
	v_cndmask_b32_e32 v140, v196, v132, vcc
	s_waitcnt lgkmcnt(0)
	v_mul_f32_e32 v128, v133, v128
	v_cndmask_b32_e64 v128, v128, -v128, s[4:5]
	v_fmac_f32_e32 v128, v129, v197
	v_cndmask_b32_e32 v141, v197, v128, vcc
	ds_bpermute_b32 v128, v173, v154
	s_waitcnt lgkmcnt(0)
; __device__ __forceinline__ u32x4 pack8(const f32x4& a, const f32x4& b) { u32x4 w; w.x = cvt_pk_bf16(a[0], a[1]); w.y = cvt_pk_bf16(a[2], a[3]); w.z = cvt_pk_bf16(b[0], b[1]); w.w = cvt_pk_bf16(b[2], b[3]); return w; }
; __device__ __forceinline__ float frsq(float x) { return __builtin_amdgcn_rsqf(x); }
;     __device__ __forceinline__ void operator()(Acc& acc, const Unit& u, int wr, int wc, int fr, int fq) const {
;     ...
;                     for (int m2 = 0; m2 < 2; ++m2) { const float* rp = rope + (size_t)(row0 + ai * HALF + (2 * mh + m2) * 16) * 16;
; #pragma unroll
;                         for (int n = 0; n < 2; ++n) { rc[m2][n] = *(const f32x4*)(rp + 4 * n); rs[m2][n] = *(const f32x4*)(rp + 8 + 4 * n); } }
;                     __builtin_amdgcn_sched_barrier(0);
; #pragma unroll
;                     for (int m2 = 0; m2 < 2; ++m2) { const int m = 2 * mh + m2;
;                         const int row = row0 + ai * HALF + m * 16;
;                         float ss = 0.f;
; #pragma unroll
;                         for (int bj = 0; bj < 2; ++bj)
; #pragma unroll
;                             for (int n = 0; n < 2; ++n) { const f32x4 v = acc[ai][bj][m][n]; ss += (v[0] * v[0] + v[1] * v[1]) + (v[2] * v[2] + v[3] * v[3]); }
;                         ss += __shfl_xor(ss, 16); ss += __shfl_xor(ss, 32);
;                         const float rstd = frsq(ss * (1.0f / 64.0f) + EPS);
;                         f32x4 y[2][2];
; #pragma unroll
;                         for (int bj = 0; bj < 2; ++bj)
; #pragma unroll
;                             for (int n = 0; n < 2; ++n) y[bj][n] = acc[ai][bj][m][n] * rstd * g[bj][n];
; #pragma unroll
;                         for (int n = 0; n < 2; ++n) {
;                             const f32x4 cs = rc[m2][n], sn = rs[m2][n];
;                             f32x4 o;
; #pragma unroll
;                             for (int i = 0; i < 4; ++i) { const float mine = y[0][n][i], oth = __shfl_xor(mine, 16);
;                                 const float r = (fq == 0) ? (mine * cs[i] - oth * sn[i]) : (mine * cs[i] + oth * sn[i]);
;                                 o[i] = (fq < 2) ? r : mine; }
;                             y[0][n] = o;
;                         }
; #pragma unroll
;                         for (int bj = 0; bj < 2; ++bj) *(u32x4*)(ob + (size_t)row * ld + bj * 32) = pack8(y[bj][0], y[bj][1]);
	v_mul_f32_e32 v128, v134, v128
	v_cndmask_b32_e64 v128, v128, -v128, s[4:5]
	v_fmac_f32_e32 v128, v130, v154
	v_cndmask_b32_e32 v134, v154, v128, vcc
	ds_bpermute_b32 v128, v173, v155
	v_add_u32_e32 v154, 0x80, v174
	s_waitcnt lgkmcnt(0)
	v_mul_f32_e32 v128, v135, v128
	v_cndmask_b32_e64 v128, v128, -v128, s[4:5]
	v_fmac_f32_e32 v128, v131, v155
	v_cndmask_b32_e32 v131, v155, v128, vcc
	v_lshlrev_b64 v[128:129], s12, v[152:153]
	v_lshl_add_u64 v[132:133], v[128:129], 1, v[178:179]
	v_cvt_pk_bf16_f32 v128, v136, v137
	v_cvt_pk_bf16_f32 v129, v138, v139
	v_cvt_pk_bf16_f32 v130, v140, v141
	v_cvt_pk_bf16_f32 v131, v134, v131
	global_store_dwordx4 v[132:133], v[128:131], off
	v_ashrrev_i32_e32 v155, 31, v154
	v_add_u32_e32 v152, 0x90, v174
	v_cvt_pk_bf16_f32 v128, v150, v151
	v_cvt_pk_bf16_f32 v129, v146, v147
	v_cvt_pk_bf16_f32 v130, v148, v149
	v_cvt_pk_bf16_f32 v131, v144, v145
	global_store_dwordx4 v[132:133], v[128:131], off offset:64
	v_ashrrev_i32_e32 v153, 31, v152
	s_nop 0
	v_mul_u32_u24_e32 v232, 0x50, v154
	v_add_u32_e32 v232, s98, v232
	ds_read_b128 v[144:147], v232 offset:16
	ds_read_b128 v[148:151], v232 offset:48
	ds_read_b128 v[202:205], v232
	ds_read_b128 v[222:225], v232 offset:32
	v_mul_u32_u24_e32 v233, 0x50, v152
	v_add_u32_e32 v233, s98, v233
	ds_read_b128 v[128:131], v233 offset:16
	ds_read_b128 v[132:135], v233 offset:48
	ds_read_b128 v[136:139], v233
	s_nop 0
	ds_read_b128 v[140:143], v233 offset:32
	v_pk_mul_f32 v[156:157], v[62:63], v[62:63]
	v_pk_mul_f32 v[158:159], v[60:61], v[60:61]
	v_mul_f32_e32 v175, v40, v40
	v_pk_mov_b32 v[196:197], v[158:159], v[156:157] op_sel:[1,0]
	v_mov_b32_e32 v159, v157
	v_pk_add_f32 v[156:157], v[196:197], v[158:159]
	v_pk_mul_f32 v[158:159], v[58:59], v[58:59]
	v_pk_mul_f32 v[196:197], v[56:57], v[56:57]
	v_pk_add_f32 v[156:157], v[156:157], v[156:157] op_sel:[0,1] op_sel_hi:[1,0]
	v_pk_mov_b32 v[198:199], v[196:197], v[158:159] op_sel:[1,0]
	v_mov_b32_e32 v197, v159
	v_pk_add_f32 v[158:159], v[198:199], v[196:197]
	v_mul_f32_e32 v196, v41, v41
	v_pk_add_f32 v[158:159], v[158:159], v[158:159] op_sel:[0,1] op_sel_hi:[1,0]
	v_mov_b32_e32 v157, v175
	v_mov_b32_e32 v159, v196
	v_pk_add_f32 v[156:157], v[156:157], v[158:159]
	v_mul_f32_e32 v158, v49, v49
	v_mul_f32_e32 v197, v42, v42
	v_pk_fma_f32 v[158:159], v[48:49], v[48:49], v[158:159] op_sel_hi:[1,1,0]
	v_mul_f32_e32 v196, v51, v51
	v_mul_f32_e32 v198, v43, v43
	v_mov_b32_e32 v159, v197
	v_pk_fma_f32 v[196:197], v[50:51], v[50:51], v[196:197] op_sel_hi:[1,1,0]
	s_nop 0
	v_mov_b32_e32 v197, v198
	v_pk_add_f32 v[158:159], v[158:159], v[196:197]
	s_nop 0
	v_pk_add_f32 v[156:157], v[156:157], v[158:159]
	s_nop 0
	v_add_f32_e32 v156, v156, v157
	ds_bpermute_b32 v157, v173, v156
	s_waitcnt lgkmcnt(0)
	v_add_f32_e32 v156, v156, v157
	ds_bpermute_b32 v157, v220, v156
	s_waitcnt lgkmcnt(0)
	v_add_f32_e32 v156, v156, v157
	v_fmamk_f32 v156, v156, 0x3c800000, v215
	v_rsq_f32_e32 v196, v156
	s_nop 0
	v_pk_mul_f32 v[156:157], v[60:61], v[196:197] op_sel_hi:[1,0]
	s_nop 0
	v_pk_mul_f32 v[226:227], v[186:187], v[156:157]
	ds_bpermute_b32 v175, v173, v226
	v_pk_mul_f32 v[158:159], v[62:63], v[196:197] op_sel_hi:[1,0]
	v_pk_mul_f32 v[156:157], v[56:57], v[196:197] op_sel_hi:[1,0]
	v_pk_mul_f32 v[206:207], v[184:185], v[158:159]
	v_pk_mul_f32 v[230:231], v[182:183], v[156:157]
	s_waitcnt vmcnt(4) lgkmcnt(0)
	v_mul_f32_e32 v175, v222, v175
	v_cndmask_b32_e64 v175, v175, -v175, s[4:5]
	v_fmac_f32_e32 v175, v202, v226
	ds_bpermute_b32 v202, v173, v227
	v_pk_mul_f32 v[158:159], v[58:59], v[196:197] op_sel_hi:[1,0]
	v_pk_mul_f32 v[156:157], v[50:51], v[196:197] op_sel_hi:[1,0]
	v_pk_mul_f32 v[200:201], v[180:181], v[158:159]
	v_pk_mul_f32 v[158:159], v[48:49], v[196:197] op_sel_hi:[1,0]
	s_waitcnt lgkmcnt(0)
	v_mul_f32_e32 v202, v223, v202
	v_cndmask_b32_e64 v202, v202, -v202, s[4:5]
	v_fmac_f32_e32 v202, v203, v227
	ds_bpermute_b32 v203, v173, v206
	v_pk_mul_f32 v[198:199], v[40:41], v[196:197] op_sel_hi:[1,0]
	v_pk_mul_f32 v[196:197], v[42:43], v[196:197] op_sel_hi:[1,0]
	v_cndmask_b32_e32 v175, v226, v175, vcc
	v_cndmask_b32_e32 v202, v227, v202, vcc
	s_waitcnt lgkmcnt(0)
	v_mul_f32_e32 v203, v224, v203
	v_cndmask_b32_e64 v203, v203, -v203, s[4:5]
	v_fmac_f32_e32 v203, v204, v206
	ds_bpermute_b32 v204, v173, v207
	v_cndmask_b32_e32 v203, v206, v203, vcc
	v_pk_mul_f32 v[156:157], v[192:193], v[156:157]
	v_pk_mul_f32 v[158:159], v[194:195], v[158:159]
	v_pk_mul_f32 v[196:197], v[188:189], v[196:197]
	s_waitcnt lgkmcnt(0)
	v_mul_f32_e32 v204, v225, v204
	v_cndmask_b32_e64 v204, v204, -v204, s[4:5]
	v_fmac_f32_e32 v204, v205, v207
	ds_bpermute_b32 v205, v173, v230
	v_cndmask_b32_e32 v204, v207, v204, vcc
	v_pk_mul_f32 v[198:199], v[190:191], v[198:199]
	s_waitcnt lgkmcnt(0)
	v_mul_f32_e32 v148, v148, v205
	v_cndmask_b32_e64 v148, v148, -v148, s[4:5]
	v_fmac_f32_e32 v148, v144, v230
	ds_bpermute_b32 v144, v173, v231
	v_cndmask_b32_e32 v205, v230, v148, vcc
	s_waitcnt lgkmcnt(0)
	v_mul_f32_e32 v144, v149, v144
	v_cndmask_b32_e64 v144, v144, -v144, s[4:5]
	v_fmac_f32_e32 v144, v145, v231
	v_cndmask_b32_e32 v206, v231, v144, vcc
	ds_bpermute_b32 v144, v173, v200
	s_waitcnt lgkmcnt(0)
	v_mul_f32_e32 v144, v150, v144
	v_cndmask_b32_e64 v144, v144, -v144, s[4:5]
	v_fmac_f32_e32 v144, v146, v200
	v_cndmask_b32_e32 v150, v200, v144, vcc
	ds_bpermute_b32 v144, v173, v201
	s_waitcnt lgkmcnt(0)
; __device__ __forceinline__ u32x4 pack8(const f32x4& a, const f32x4& b) { u32x4 w; w.x = cvt_pk_bf16(a[0], a[1]); w.y = cvt_pk_bf16(a[2], a[3]); w.z = cvt_pk_bf16(b[0], b[1]); w.w = cvt_pk_bf16(b[2], b[3]); return w; }
; __device__ __forceinline__ float frsq(float x) { return __builtin_amdgcn_rsqf(x); }
;     __device__ __forceinline__ void operator()(Acc& acc, const Unit& u, int wr, int wc, int fr, int fq) const {
;     ...
;                     for (int m2 = 0; m2 < 2; ++m2) { const int m = 2 * mh + m2;
;                         const int row = row0 + ai * HALF + m * 16;
;                         float ss = 0.f;
; #pragma unroll
;                         for (int bj = 0; bj < 2; ++bj)
; #pragma unroll
;                             for (int n = 0; n < 2; ++n) { const f32x4 v = acc[ai][bj][m][n]; ss += (v[0] * v[0] + v[1] * v[1]) + (v[2] * v[2] + v[3] * v[3]); }
;                         ss += __shfl_xor(ss, 16); ss += __shfl_xor(ss, 32);
;                         const float rstd = frsq(ss * (1.0f / 64.0f) + EPS);
;                         f32x4 y[2][2];
; #pragma unroll
;                         for (int bj = 0; bj < 2; ++bj)
; #pragma unroll
;                             for (int n = 0; n < 2; ++n) y[bj][n] = acc[ai][bj][m][n] * rstd * g[bj][n];
; #pragma unroll
;                         for (int n = 0; n < 2; ++n) {
;                             const f32x4 cs = rc[m2][n], sn = rs[m2][n];
;                             f32x4 o;
; #pragma unroll
;                             for (int i = 0; i < 4; ++i) { const float mine = y[0][n][i], oth = __shfl_xor(mine, 16);
;                                 const float r = (fq == 0) ? (mine * cs[i] - oth * sn[i]) : (mine * cs[i] + oth * sn[i]);
;                                 o[i] = (fq < 2) ? r : mine; }
;                             y[0][n] = o;
;                         }
; #pragma unroll
;                         for (int bj = 0; bj < 2; ++bj) *(u32x4*)(ob + (size_t)row * ld + bj * 32) = pack8(y[bj][0], y[bj][1]);
	v_mul_f32_e32 v144, v151, v144
	v_cndmask_b32_e64 v144, v144, -v144, s[4:5]
	v_fmac_f32_e32 v144, v147, v201
	v_cndmask_b32_e32 v147, v201, v144, vcc
	v_lshlrev_b64 v[144:145], s12, v[154:155]
	v_lshl_add_u64 v[148:149], v[144:145], 1, v[178:179]
	v_cvt_pk_bf16_f32 v144, v175, v202
	v_cvt_pk_bf16_f32 v145, v203, v204
	v_cvt_pk_bf16_f32 v146, v205, v206
	v_cvt_pk_bf16_f32 v147, v150, v147
	global_store_dwordx4 v[148:149], v[144:147], off
	s_nop 1
	v_cvt_pk_bf16_f32 v144, v158, v159
	v_cvt_pk_bf16_f32 v145, v156, v157
	v_cvt_pk_bf16_f32 v146, v198, v199
	v_cvt_pk_bf16_f32 v147, v196, v197
	global_store_dwordx4 v[148:149], v[144:147], off offset:64
	s_nop 1
	v_pk_mul_f32 v[144:145], v[54:55], v[54:55]
	v_pk_mul_f32 v[146:147], v[52:53], v[52:53]
	s_nop 0
	v_pk_mov_b32 v[148:149], v[146:147], v[144:145] op_sel:[1,0]
	v_mov_b32_e32 v147, v145
	v_pk_add_f32 v[144:145], v[148:149], v[146:147]
	v_pk_mul_f32 v[146:147], v[46:47], v[46:47]
	v_pk_mul_f32 v[148:149], v[44:45], v[44:45]
	v_pk_add_f32 v[144:145], v[144:145], v[144:145] op_sel:[0,1] op_sel_hi:[1,0]
	v_pk_mov_b32 v[150:151], v[148:149], v[146:147] op_sel:[1,0]
	v_mov_b32_e32 v149, v147
	v_pk_add_f32 v[146:147], v[150:151], v[148:149]
	v_mul_f32_e32 v148, v24, v24
	v_mul_f32_e32 v149, v25, v25
	v_pk_add_f32 v[146:147], v[146:147], v[146:147] op_sel:[0,1] op_sel_hi:[1,0]
	v_mov_b32_e32 v145, v148
	v_mov_b32_e32 v147, v149
	v_pk_add_f32 v[144:145], v[144:145], v[146:147]
	v_mul_f32_e32 v146, v33, v33
	v_mul_f32_e32 v148, v35, v35
	v_mul_f32_e32 v150, v26, v26
	v_mul_f32_e32 v151, v27, v27
	v_pk_fma_f32 v[146:147], v[32:33], v[32:33], v[146:147] op_sel_hi:[1,1,0]
	v_pk_fma_f32 v[148:149], v[34:35], v[34:35], v[148:149] op_sel_hi:[1,1,0]
	v_mov_b32_e32 v147, v150
	v_mov_b32_e32 v149, v151
	v_pk_add_f32 v[146:147], v[146:147], v[148:149]
	s_nop 0
	v_pk_add_f32 v[144:145], v[144:145], v[146:147]
	s_nop 0
	v_add_f32_e32 v144, v144, v145
	ds_bpermute_b32 v145, v173, v144
	s_waitcnt lgkmcnt(0)
	v_add_f32_e32 v144, v144, v145
	ds_bpermute_b32 v145, v220, v144
	s_waitcnt lgkmcnt(0)
	v_add_f32_e32 v144, v144, v145
	v_fmamk_f32 v144, v144, 0x3c800000, v215
	v_rsq_f32_e32 v144, v144
	s_nop 0
	v_pk_mul_f32 v[146:147], v[52:53], v[144:145] op_sel_hi:[1,0]
	s_nop 0
	v_pk_mul_f32 v[158:159], v[186:187], v[146:147]
	ds_bpermute_b32 v175, v173, v158
	v_pk_mul_f32 v[148:149], v[54:55], v[144:145] op_sel_hi:[1,0]
	v_pk_mul_f32 v[146:147], v[44:45], v[144:145] op_sel_hi:[1,0]
	v_pk_mul_f32 v[156:157], v[184:185], v[148:149]
	v_pk_mul_f32 v[196:197], v[182:183], v[146:147]
	s_waitcnt vmcnt(2) lgkmcnt(0)
	v_mul_f32_e32 v140, v140, v175
	v_cndmask_b32_e64 v140, v140, -v140, s[4:5]
	v_fmac_f32_e32 v140, v136, v158
	v_cndmask_b32_e32 v136, v158, v140, vcc
	ds_bpermute_b32 v140, v173, v159
	v_pk_mul_f32 v[148:149], v[46:47], v[144:145] op_sel_hi:[1,0]
	v_pk_mul_f32 v[146:147], v[34:35], v[144:145] op_sel_hi:[1,0]
	v_pk_mul_f32 v[154:155], v[180:181], v[148:149]
	v_pk_mul_f32 v[148:149], v[32:33], v[144:145] op_sel_hi:[1,0]
	s_waitcnt lgkmcnt(0)
	v_mul_f32_e32 v140, v141, v140
	v_cndmask_b32_e64 v140, v140, -v140, s[4:5]
	v_fmac_f32_e32 v140, v137, v159
	v_cndmask_b32_e32 v137, v159, v140, vcc
	ds_bpermute_b32 v140, v173, v156
	v_pk_mul_f32 v[146:147], v[192:193], v[146:147]
	v_pk_mul_f32 v[150:151], v[194:195], v[148:149]
	v_pk_mul_f32 v[148:149], v[24:25], v[144:145] op_sel_hi:[1,0]
	v_pk_mul_f32 v[144:145], v[26:27], v[144:145] op_sel_hi:[1,0]
	s_waitcnt lgkmcnt(0)
	v_mul_f32_e32 v140, v142, v140
	v_cndmask_b32_e64 v140, v140, -v140, s[4:5]
	v_fmac_f32_e32 v140, v138, v156
	v_cndmask_b32_e32 v138, v156, v140, vcc
	ds_bpermute_b32 v140, v173, v157
	v_pk_mul_f32 v[144:145], v[188:189], v[144:145]
	v_pk_mul_f32 v[148:149], v[190:191], v[148:149]
	s_waitcnt lgkmcnt(0)
	v_mul_f32_e32 v140, v143, v140
	v_cndmask_b32_e64 v140, v140, -v140, s[4:5]
	v_fmac_f32_e32 v140, v139, v157
	v_cndmask_b32_e32 v139, v157, v140, vcc
	ds_bpermute_b32 v140, v173, v196
	s_waitcnt lgkmcnt(0)
	v_mul_f32_e32 v132, v132, v140
	v_cndmask_b32_e64 v132, v132, -v132, s[4:5]
	v_fmac_f32_e32 v132, v128, v196
	ds_bpermute_b32 v128, v173, v197
	v_cndmask_b32_e32 v140, v196, v132, vcc
	s_waitcnt lgkmcnt(0)
	v_mul_f32_e32 v128, v133, v128
	v_cndmask_b32_e64 v128, v128, -v128, s[4:5]
	v_fmac_f32_e32 v128, v129, v197
	v_cndmask_b32_e32 v141, v197, v128, vcc
	ds_bpermute_b32 v128, v173, v154
	s_waitcnt lgkmcnt(0)
	v_mul_f32_e32 v128, v134, v128
	v_cndmask_b32_e64 v128, v128, -v128, s[4:5]
	v_fmac_f32_e32 v128, v130, v154
	v_cndmask_b32_e32 v134, v154, v128, vcc
	ds_bpermute_b32 v128, v173, v155
	v_add_u32_e32 v154, 0xa0, v174
	s_waitcnt lgkmcnt(0)
; __device__ __forceinline__ u32x4 pack8(const f32x4& a, const f32x4& b) { u32x4 w; w.x = cvt_pk_bf16(a[0], a[1]); w.y = cvt_pk_bf16(a[2], a[3]); w.z = cvt_pk_bf16(b[0], b[1]); w.w = cvt_pk_bf16(b[2], b[3]); return w; }
; __device__ __forceinline__ float frsq(float x) { return __builtin_amdgcn_rsqf(x); }
;     __device__ __forceinline__ void operator()(Acc& acc, const Unit& u, int wr, int wc, int fr, int fq) const {
;     ...
;                     for (int m2 = 0; m2 < 2; ++m2) { const float* rp = rope + (size_t)(row0 + ai * HALF + (2 * mh + m2) * 16) * 16;
; #pragma unroll
;                         for (int n = 0; n < 2; ++n) { rc[m2][n] = *(const f32x4*)(rp + 4 * n); rs[m2][n] = *(const f32x4*)(rp + 8 + 4 * n); } }
;                     __builtin_amdgcn_sched_barrier(0);
; #pragma unroll
;                     for (int m2 = 0; m2 < 2; ++m2) { const int m = 2 * mh + m2;
;                         const int row = row0 + ai * HALF + m * 16;
;                         float ss = 0.f;
; #pragma unroll
;                         for (int bj = 0; bj < 2; ++bj)
; #pragma unroll
;                             for (int n = 0; n < 2; ++n) { const f32x4 v = acc[ai][bj][m][n]; ss += (v[0] * v[0] + v[1] * v[1]) + (v[2] * v[2] + v[3] * v[3]); }
;                         ss += __shfl_xor(ss, 16); ss += __shfl_xor(ss, 32);
;                         const float rstd = frsq(ss * (1.0f / 64.0f) + EPS);
;                         f32x4 y[2][2];
; #pragma unroll
;                         for (int bj = 0; bj < 2; ++bj)
; #pragma unroll
;                             for (int n = 0; n < 2; ++n) y[bj][n] = acc[ai][bj][m][n] * rstd * g[bj][n];
; #pragma unroll
;                         for (int n = 0; n < 2; ++n) {
;                             const f32x4 cs = rc[m2][n], sn = rs[m2][n];
;                             f32x4 o;
; #pragma unroll
;                             for (int i = 0; i < 4; ++i) { const float mine = y[0][n][i], oth = __shfl_xor(mine, 16);
;                                 const float r = (fq == 0) ? (mine * cs[i] - oth * sn[i]) : (mine * cs[i] + oth * sn[i]);
;                                 o[i] = (fq < 2) ? r : mine; }
;                             y[0][n] = o;
;                         }
; #pragma unroll
;                         for (int bj = 0; bj < 2; ++bj) *(u32x4*)(ob + (size_t)row * ld + bj * 32) = pack8(y[bj][0], y[bj][1]);
	v_mul_f32_e32 v128, v135, v128
	v_cndmask_b32_e64 v128, v128, -v128, s[4:5]
	v_fmac_f32_e32 v128, v131, v155
	v_cndmask_b32_e32 v131, v155, v128, vcc
	v_lshlrev_b64 v[128:129], s12, v[152:153]
	v_lshl_add_u64 v[132:133], v[128:129], 1, v[178:179]
	v_cvt_pk_bf16_f32 v128, v136, v137
	v_cvt_pk_bf16_f32 v129, v138, v139
	v_cvt_pk_bf16_f32 v130, v140, v141
	v_cvt_pk_bf16_f32 v131, v134, v131
	global_store_dwordx4 v[132:133], v[128:131], off
	v_ashrrev_i32_e32 v155, 31, v154
	v_add_u32_e32 v152, 0xb0, v174
	v_cvt_pk_bf16_f32 v128, v150, v151
	v_cvt_pk_bf16_f32 v129, v146, v147
	v_cvt_pk_bf16_f32 v130, v148, v149
	v_cvt_pk_bf16_f32 v131, v144, v145
	global_store_dwordx4 v[132:133], v[128:131], off offset:64
	v_ashrrev_i32_e32 v153, 31, v152
	s_nop 0
	v_mul_u32_u24_e32 v232, 0x50, v154
	v_add_u32_e32 v232, s98, v232
	ds_read_b128 v[144:147], v232 offset:16
	ds_read_b128 v[148:151], v232 offset:48
	ds_read_b128 v[202:205], v232
	ds_read_b128 v[222:225], v232 offset:32
	v_mul_u32_u24_e32 v233, 0x50, v152
	v_add_u32_e32 v233, s98, v233
	ds_read_b128 v[128:131], v233 offset:16
	ds_read_b128 v[132:135], v233 offset:48
	ds_read_b128 v[136:139], v233
	s_nop 0
	ds_read_b128 v[140:143], v233 offset:32
	v_pk_mul_f32 v[156:157], v[38:39], v[38:39]
	v_pk_mul_f32 v[158:159], v[36:37], v[36:37]
	v_mul_f32_e32 v175, v8, v8
	v_pk_mov_b32 v[196:197], v[158:159], v[156:157] op_sel:[1,0]
	v_mov_b32_e32 v159, v157
	v_pk_add_f32 v[156:157], v[196:197], v[158:159]
	v_pk_mul_f32 v[158:159], v[30:31], v[30:31]
	v_pk_mul_f32 v[196:197], v[28:29], v[28:29]
	v_pk_add_f32 v[156:157], v[156:157], v[156:157] op_sel:[0,1] op_sel_hi:[1,0]
	v_pk_mov_b32 v[198:199], v[196:197], v[158:159] op_sel:[1,0]
	v_mov_b32_e32 v197, v159
	v_pk_add_f32 v[158:159], v[198:199], v[196:197]
	v_mul_f32_e32 v196, v9, v9
	v_pk_add_f32 v[158:159], v[158:159], v[158:159] op_sel:[0,1] op_sel_hi:[1,0]
	v_mov_b32_e32 v157, v175
	v_mov_b32_e32 v159, v196
	v_pk_add_f32 v[156:157], v[156:157], v[158:159]
	v_mul_f32_e32 v158, v17, v17
	v_mul_f32_e32 v197, v10, v10
	v_pk_fma_f32 v[158:159], v[16:17], v[16:17], v[158:159] op_sel_hi:[1,1,0]
	v_mul_f32_e32 v196, v19, v19
	v_mul_f32_e32 v198, v11, v11
	v_mov_b32_e32 v159, v197
	v_pk_fma_f32 v[196:197], v[18:19], v[18:19], v[196:197] op_sel_hi:[1,1,0]
	s_nop 0
	v_mov_b32_e32 v197, v198
	v_pk_add_f32 v[158:159], v[158:159], v[196:197]
	s_nop 0
	v_pk_add_f32 v[156:157], v[156:157], v[158:159]
	s_nop 0
	v_add_f32_e32 v156, v156, v157
	ds_bpermute_b32 v157, v173, v156
	s_waitcnt lgkmcnt(0)
	v_add_f32_e32 v156, v156, v157
	ds_bpermute_b32 v157, v220, v156
	s_waitcnt lgkmcnt(0)
	v_add_f32_e32 v156, v156, v157
	v_fmamk_f32 v156, v156, 0x3c800000, v215
	v_rsq_f32_e32 v196, v156
	s_nop 0
	v_pk_mul_f32 v[156:157], v[36:37], v[196:197] op_sel_hi:[1,0]
	s_nop 0
	v_pk_mul_f32 v[226:227], v[186:187], v[156:157]
	ds_bpermute_b32 v175, v173, v226
	v_pk_mul_f32 v[158:159], v[38:39], v[196:197] op_sel_hi:[1,0]
	v_pk_mul_f32 v[156:157], v[28:29], v[196:197] op_sel_hi:[1,0]
	v_pk_mul_f32 v[206:207], v[184:185], v[158:159]
	v_pk_mul_f32 v[230:231], v[182:183], v[156:157]
	s_waitcnt vmcnt(4) lgkmcnt(0)
	v_mul_f32_e32 v175, v222, v175
	v_cndmask_b32_e64 v175, v175, -v175, s[4:5]
	v_fmac_f32_e32 v175, v202, v226
	ds_bpermute_b32 v202, v173, v227
	v_pk_mul_f32 v[158:159], v[30:31], v[196:197] op_sel_hi:[1,0]
	v_pk_mul_f32 v[156:157], v[18:19], v[196:197] op_sel_hi:[1,0]
	v_pk_mul_f32 v[200:201], v[180:181], v[158:159]
	v_pk_mul_f32 v[158:159], v[16:17], v[196:197] op_sel_hi:[1,0]
	s_waitcnt lgkmcnt(0)
	v_mul_f32_e32 v202, v223, v202
	v_cndmask_b32_e64 v202, v202, -v202, s[4:5]
	v_fmac_f32_e32 v202, v203, v227
	ds_bpermute_b32 v203, v173, v206
	v_pk_mul_f32 v[198:199], v[8:9], v[196:197] op_sel_hi:[1,0]
	v_pk_mul_f32 v[196:197], v[10:11], v[196:197] op_sel_hi:[1,0]
	v_cndmask_b32_e32 v175, v226, v175, vcc
	v_cndmask_b32_e32 v202, v227, v202, vcc
	s_waitcnt lgkmcnt(0)
	v_mul_f32_e32 v203, v224, v203
	v_cndmask_b32_e64 v203, v203, -v203, s[4:5]
	v_fmac_f32_e32 v203, v204, v206
	ds_bpermute_b32 v204, v173, v207
	v_cndmask_b32_e32 v203, v206, v203, vcc
	v_pk_mul_f32 v[156:157], v[192:193], v[156:157]
	v_pk_mul_f32 v[158:159], v[194:195], v[158:159]
	v_pk_mul_f32 v[196:197], v[188:189], v[196:197]
	s_waitcnt lgkmcnt(0)
	v_mul_f32_e32 v204, v225, v204
	v_cndmask_b32_e64 v204, v204, -v204, s[4:5]
	v_fmac_f32_e32 v204, v205, v207
	ds_bpermute_b32 v205, v173, v230
	v_cndmask_b32_e32 v204, v207, v204, vcc
	v_pk_mul_f32 v[198:199], v[190:191], v[198:199]
	s_waitcnt lgkmcnt(0)
	v_mul_f32_e32 v148, v148, v205
	v_cndmask_b32_e64 v148, v148, -v148, s[4:5]
	v_fmac_f32_e32 v148, v144, v230
	ds_bpermute_b32 v144, v173, v231
	v_cndmask_b32_e32 v205, v230, v148, vcc
	s_waitcnt lgkmcnt(0)
	v_mul_f32_e32 v144, v149, v144
	v_cndmask_b32_e64 v144, v144, -v144, s[4:5]
	v_fmac_f32_e32 v144, v145, v231
	v_cndmask_b32_e32 v206, v231, v144, vcc
	ds_bpermute_b32 v144, v173, v200
	s_waitcnt lgkmcnt(0)
	v_mul_f32_e32 v144, v150, v144
	v_cndmask_b32_e64 v144, v144, -v144, s[4:5]
	v_fmac_f32_e32 v144, v146, v200
	v_cndmask_b32_e32 v150, v200, v144, vcc
	ds_bpermute_b32 v144, v173, v201
	s_waitcnt lgkmcnt(0)
; __device__ __forceinline__ u32x4 pack8(const f32x4& a, const f32x4& b) { u32x4 w; w.x = cvt_pk_bf16(a[0], a[1]); w.y = cvt_pk_bf16(a[2], a[3]); w.z = cvt_pk_bf16(b[0], b[1]); w.w = cvt_pk_bf16(b[2], b[3]); return w; }
; __device__ __forceinline__ float frsq(float x) { return __builtin_amdgcn_rsqf(x); }
;     __device__ __forceinline__ void operator()(Acc& acc, const Unit& u, int wr, int wc, int fr, int fq) const {
;     ...
;                     for (int m2 = 0; m2 < 2; ++m2) { const int m = 2 * mh + m2;
;                         const int row = row0 + ai * HALF + m * 16;
;                         float ss = 0.f;
; #pragma unroll
;                         for (int bj = 0; bj < 2; ++bj)
; #pragma unroll
;                             for (int n = 0; n < 2; ++n) { const f32x4 v = acc[ai][bj][m][n]; ss += (v[0] * v[0] + v[1] * v[1]) + (v[2] * v[2] + v[3] * v[3]); }
;                         ss += __shfl_xor(ss, 16); ss += __shfl_xor(ss, 32);
;                         const float rstd = frsq(ss * (1.0f / 64.0f) + EPS);
;                         f32x4 y[2][2];
; #pragma unroll
;                         for (int bj = 0; bj < 2; ++bj)
; #pragma unroll
;                             for (int n = 0; n < 2; ++n) y[bj][n] = acc[ai][bj][m][n] * rstd * g[bj][n];
; #pragma unroll
;                         for (int n = 0; n < 2; ++n) {
;                             const f32x4 cs = rc[m2][n], sn = rs[m2][n];
;                             f32x4 o;
; #pragma unroll
;                             for (int i = 0; i < 4; ++i) { const float mine = y[0][n][i], oth = __shfl_xor(mine, 16);
;                                 const float r = (fq == 0) ? (mine * cs[i] - oth * sn[i]) : (mine * cs[i] + oth * sn[i]);
;                                 o[i] = (fq < 2) ? r : mine; }
;                             y[0][n] = o;
;                         }
; #pragma unroll
;                         for (int bj = 0; bj < 2; ++bj) *(u32x4*)(ob + (size_t)row * ld + bj * 32) = pack8(y[bj][0], y[bj][1]);
	v_mul_f32_e32 v144, v151, v144
	v_cndmask_b32_e64 v144, v144, -v144, s[4:5]
	v_fmac_f32_e32 v144, v147, v201
	v_cndmask_b32_e32 v147, v201, v144, vcc
	v_lshlrev_b64 v[144:145], s12, v[154:155]
	v_lshl_add_u64 v[148:149], v[144:145], 1, v[178:179]
	v_cvt_pk_bf16_f32 v144, v175, v202
	v_cvt_pk_bf16_f32 v145, v203, v204
	v_cvt_pk_bf16_f32 v146, v205, v206
	v_cvt_pk_bf16_f32 v147, v150, v147
	global_store_dwordx4 v[148:149], v[144:147], off
	s_nop 1
	v_cvt_pk_bf16_f32 v144, v158, v159
	v_cvt_pk_bf16_f32 v145, v156, v157
	v_cvt_pk_bf16_f32 v146, v198, v199
	v_cvt_pk_bf16_f32 v147, v196, v197
	global_store_dwordx4 v[148:149], v[144:147], off offset:64
	s_nop 1
	v_pk_mul_f32 v[144:145], v[22:23], v[22:23]
	v_pk_mul_f32 v[146:147], v[20:21], v[20:21]
	s_nop 0
	v_pk_mov_b32 v[148:149], v[146:147], v[144:145] op_sel:[1,0]
	v_mov_b32_e32 v147, v145
	v_pk_add_f32 v[144:145], v[148:149], v[146:147]
	v_pk_mul_f32 v[146:147], v[14:15], v[14:15]
	v_pk_mul_f32 v[148:149], v[12:13], v[12:13]
	v_pk_add_f32 v[144:145], v[144:145], v[144:145] op_sel:[0,1] op_sel_hi:[1,0]
	v_pk_mov_b32 v[150:151], v[148:149], v[146:147] op_sel:[1,0]
	v_mov_b32_e32 v149, v147
	v_pk_add_f32 v[146:147], v[150:151], v[148:149]
	v_mul_f32_e32 v148, v0, v0
	v_mul_f32_e32 v149, v1, v1
	v_pk_add_f32 v[146:147], v[146:147], v[146:147] op_sel:[0,1] op_sel_hi:[1,0]
	v_mov_b32_e32 v145, v148
	v_mov_b32_e32 v147, v149
	v_pk_add_f32 v[144:145], v[144:145], v[146:147]
	v_mul_f32_e32 v146, v5, v5
	v_mul_f32_e32 v148, v7, v7
	v_mul_f32_e32 v150, v2, v2
	v_mul_f32_e32 v151, v3, v3
	v_pk_fma_f32 v[146:147], v[4:5], v[4:5], v[146:147] op_sel_hi:[1,1,0]
	v_pk_fma_f32 v[148:149], v[6:7], v[6:7], v[148:149] op_sel_hi:[1,1,0]
	v_mov_b32_e32 v147, v150
	v_mov_b32_e32 v149, v151
	v_pk_add_f32 v[146:147], v[146:147], v[148:149]
	s_nop 0
	v_pk_add_f32 v[144:145], v[144:145], v[146:147]
	s_nop 0
	v_add_f32_e32 v144, v144, v145
	ds_bpermute_b32 v145, v173, v144
	s_waitcnt lgkmcnt(0)
	v_add_f32_e32 v144, v144, v145
	ds_bpermute_b32 v145, v220, v144
	s_waitcnt lgkmcnt(0)
	v_add_f32_e32 v144, v144, v145
	v_fmamk_f32 v144, v144, 0x3c800000, v215
	v_rsq_f32_e32 v144, v144
	s_nop 0
	v_pk_mul_f32 v[146:147], v[20:21], v[144:145] op_sel_hi:[1,0]
	s_nop 0
	v_pk_mul_f32 v[158:159], v[186:187], v[146:147]
	ds_bpermute_b32 v175, v173, v158
	v_pk_mul_f32 v[148:149], v[22:23], v[144:145] op_sel_hi:[1,0]
	v_pk_mul_f32 v[146:147], v[12:13], v[144:145] op_sel_hi:[1,0]
	v_pk_mul_f32 v[156:157], v[184:185], v[148:149]
	v_pk_mul_f32 v[148:149], v[14:15], v[144:145] op_sel_hi:[1,0]
	s_waitcnt vmcnt(2) lgkmcnt(0)
	v_mul_f32_e32 v140, v140, v175
	v_cndmask_b32_e64 v140, v140, -v140, s[4:5]
	v_fmac_f32_e32 v140, v136, v158
	v_cndmask_b32_e32 v136, v158, v140, vcc
	ds_bpermute_b32 v140, v173, v159
	v_pk_mul_f32 v[154:155], v[180:181], v[148:149]
	v_pk_mul_f32 v[180:181], v[182:183], v[146:147]
	v_pk_mul_f32 v[148:149], v[4:5], v[144:145] op_sel_hi:[1,0]
	v_pk_mul_f32 v[146:147], v[6:7], v[144:145] op_sel_hi:[1,0]
	s_waitcnt lgkmcnt(0)
	v_mul_f32_e32 v140, v141, v140
	v_cndmask_b32_e64 v140, v140, -v140, s[4:5]
	v_fmac_f32_e32 v140, v137, v159
	v_cndmask_b32_e32 v137, v159, v140, vcc
	ds_bpermute_b32 v140, v173, v156
	v_pk_mul_f32 v[150:151], v[194:195], v[148:149]
	v_pk_mul_f32 v[148:149], v[0:1], v[144:145] op_sel_hi:[1,0]
	v_pk_mul_f32 v[144:145], v[2:3], v[144:145] op_sel_hi:[1,0]
	v_pk_mul_f32 v[146:147], v[192:193], v[146:147]
	s_waitcnt lgkmcnt(0)
	v_mul_f32_e32 v140, v142, v140
	v_cndmask_b32_e64 v140, v140, -v140, s[4:5]
	v_fmac_f32_e32 v140, v138, v156
	v_cndmask_b32_e32 v138, v156, v140, vcc
	ds_bpermute_b32 v140, v173, v157
	v_pk_mul_f32 v[144:145], v[188:189], v[144:145]
	v_pk_mul_f32 v[148:149], v[190:191], v[148:149]
	s_waitcnt lgkmcnt(0)
	v_mul_f32_e32 v140, v143, v140
	v_cndmask_b32_e64 v140, v140, -v140, s[4:5]
	v_fmac_f32_e32 v140, v139, v157
	v_cndmask_b32_e32 v139, v157, v140, vcc
	ds_bpermute_b32 v140, v173, v180
	s_waitcnt lgkmcnt(0)
	v_mul_f32_e32 v132, v132, v140
	v_cndmask_b32_e64 v132, v132, -v132, s[4:5]
	v_fmac_f32_e32 v132, v128, v180
	ds_bpermute_b32 v128, v173, v181
	v_cndmask_b32_e32 v140, v180, v132, vcc
	s_waitcnt lgkmcnt(0)
	v_mul_f32_e32 v128, v133, v128
	v_cndmask_b32_e64 v128, v128, -v128, s[4:5]
	v_fmac_f32_e32 v128, v129, v181
	v_cndmask_b32_e32 v141, v181, v128, vcc
	ds_bpermute_b32 v128, v173, v154
	s_waitcnt lgkmcnt(0)
	v_mul_f32_e32 v128, v134, v128
	v_cndmask_b32_e64 v128, v128, -v128, s[4:5]
	v_fmac_f32_e32 v128, v130, v154
	v_cndmask_b32_e32 v134, v154, v128, vcc
	ds_bpermute_b32 v128, v173, v155
	s_waitcnt lgkmcnt(0)
	v_mul_f32_e32 v128, v135, v128
	v_cndmask_b32_e64 v128, v128, -v128, s[4:5]
	v_fmac_f32_e32 v128, v131, v155
	v_cndmask_b32_e32 v131, v155, v128, vcc
	v_lshlrev_b64 v[128:129], s12, v[152:153]
	v_lshl_add_u64 v[132:133], v[128:129], 1, v[178:179]
	v_cvt_pk_bf16_f32 v128, v136, v137
	v_cvt_pk_bf16_f32 v129, v138, v139
	v_cvt_pk_bf16_f32 v130, v140, v141
	v_cvt_pk_bf16_f32 v131, v134, v131
	global_store_dwordx4 v[132:133], v[128:131], off
	s_mov_b64 s[4:5], 0
	s_nop 0
	v_cvt_pk_bf16_f32 v128, v150, v151
	v_cvt_pk_bf16_f32 v129, v146, v147
	v_cvt_pk_bf16_f32 v130, v148, v149
	v_cvt_pk_bf16_f32 v131, v144, v145
	global_store_dwordx4 v[132:133], v[128:131], off offset:64

; #define LAS __attribute__((address_space(3)))
; __global__ void __launch_bounds__(512, 2) layer_fwd(Args args) {
;     extern __shared__ __attribute__((aligned(16))) unsigned char lds_raw[];
;     Frame F;
;     F.lds = (LAS unsigned char*)lds_raw; F.tid = threadIdx.x; F.lane = F.tid & 63; F.wave = __builtin_amdgcn_readfirstlane(F.tid >> 6); F.G = gridDim.x; F.bid = blockIdx.x;
	.amdhsa_kernel _Z9layer_fwd4Args
		.amdhsa_group_segment_fixed_size 0
		.amdhsa_private_segment_fixed_size 0
		.amdhsa_kernarg_size 448
		.amdhsa_user_sgpr_count 2
		.amdhsa_user_sgpr_dispatch_ptr 0
		.amdhsa_user_sgpr_queue_ptr 0
		.amdhsa_user_sgpr_kernarg_segment_ptr 1
		.amdhsa_user_sgpr_dispatch_id 0
		.amdhsa_user_sgpr_kernarg_preload_length 0
		.amdhsa_user_sgpr_kernarg_preload_offset 0
		.amdhsa_user_sgpr_private_segment_size 0
		.amdhsa_uses_dynamic_stack 0
		.amdhsa_enable_private_segment 0
		.amdhsa_system_sgpr_workgroup_id_x 1
		.amdhsa_system_sgpr_workgroup_id_y 0
		.amdhsa_system_sgpr_workgroup_id_z 0
		.amdhsa_system_sgpr_workgroup_info 0
		.amdhsa_system_vgpr_workitem_id 2
		.amdhsa_next_free_vgpr 256
		.amdhsa_next_free_sgpr 102
		.amdhsa_accum_offset 256
		.amdhsa_reserve_vcc 1
		.amdhsa_float_round_mode_32 0
		.amdhsa_float_round_mode_16_64 0
		.amdhsa_float_denorm_mode_32 3
		.amdhsa_float_denorm_mode_16_64 3
		.amdhsa_dx10_clamp 1
		.amdhsa_ieee_mode 1
		.amdhsa_fp16_overflow 0
		.amdhsa_tg_split 0
		.amdhsa_exception_fp_ieee_invalid_op 0
		.amdhsa_exception_fp_denorm_src 0
		.amdhsa_exception_fp_ieee_div_zero 0
		.amdhsa_exception_fp_ieee_overflow 0
		.amdhsa_exception_fp_ieee_underflow 0
		.amdhsa_exception_fp_ieee_inexact 0
		.amdhsa_exception_int_div_zero 0
	.end_amdhsa_kernel

; __global__ void __launch_bounds__(512, 2) layer_fwd(Args args) {
;     extern __shared__ __attribute__((aligned(16))) unsigned char lds_raw[];
amdhsa.kernels:
  - .agpr_count:     0
    .args:
      - .offset:         0
        .size:           192
        .value_kind:     by_value
      - .offset:         192
        .size:           4
        .value_kind:     hidden_block_count_x
      - .offset:         196
        .size:           4
        .value_kind:     hidden_block_count_y
      - .offset:         200
        .size:           4
        .value_kind:     hidden_block_count_z
      - .offset:         204
        .size:           2
        .value_kind:     hidden_group_size_x
      - .offset:         206
        .size:           2
        .value_kind:     hidden_group_size_y
      - .offset:         208
        .size:           2
        .value_kind:     hidden_group_size_z
      - .offset:         210
        .size:           2
        .value_kind:     hidden_remainder_x
      - .offset:         212
        .size:           2
        .value_kind:     hidden_remainder_y
      - .offset:         214
        .size:           2
        .value_kind:     hidden_remainder_z
      - .offset:         232
        .size:           8
        .value_kind:     hidden_global_offset_x
      - .offset:         240
        .size:           8
        .value_kind:     hidden_global_offset_y
      - .offset:         248
        .size:           8
        .value_kind:     hidden_global_offset_z
      - .offset:         256
        .size:           2
        .value_kind:     hidden_grid_dims
      - .offset:         280
        .size:           8
        .value_kind:     hidden_multigrid_sync_arg
      - .offset:         312
        .size:           4
        .value_kind:     hidden_dynamic_lds_size
    .group_segment_fixed_size: 0
    .kernarg_segment_align: 8
    .kernarg_segment_size: 448
    .language:       OpenCL C
    .language_version:
      - 2
      - 0
    .max_flat_workgroup_size: 512
    .name:           _Z9layer_fwd4Args
    .private_segment_fixed_size: 0
    .sgpr_count:     108
    .sgpr_spill_count: 90
    .symbol:         _Z9layer_fwd4Args.kd
    .uniform_work_group_size: 1
    .uses_dynamic_stack: false
    .vgpr_count:     256
    .vgpr_spill_count: 0
    .wavefront_size: 64
